# P9 epilogue stores write-through (sc0 sc1) so the XCD leader's buffer_wbl2 at the following grid barrier has no dirty lines left to flush
# speedup vs baseline: 1.0784x; 1.0074x over previous
.LBB0_1429:
	v_lshl_add_u32 v148, s2, 8, v152
	v_ashrrev_i32_e32 v149, 31, v148
	v_lshl_add_u64 v[144:145], v[148:149], 2, s[8:9]
	global_load_dword v164, v[144:145], off
	v_lshl_or_b32 v146, s3, 8, v154
	v_ashrrev_i32_e32 v147, 31, v146
	v_lshlrev_b64 v[150:151], 1, v[146:147]
	v_lshlrev_b64 v[162:163], 14, v[148:149]
	v_or_b32_e32 v160, 16, v148
	v_ashrrev_i32_e32 v161, 31, v160
	s_waitcnt vmcnt(0)
	v_fmamk_f32 v146, v164, 0x3a000000, v159
	v_mul_f32_e32 v147, 0x4b800000, v146
	v_cmp_gt_f32_e32 vcc, s56, v146
	s_nop 1
	v_cndmask_b32_e32 v146, v146, v147, vcc
	v_rsq_f32_e32 v149, v146
	v_lshl_add_u64 v[146:147], s[6:7], 0, v[162:163]
	v_lshl_add_u64 v[146:147], v[146:147], 0, v[150:151]
	v_lshl_add_u64 v[162:163], v[160:161], 2, s[8:9]
	v_mul_f32_e32 v164, 0x45800000, v149
	v_cndmask_b32_e32 v164, v149, v164, vcc
	v_pk_mul_f32 v[126:127], v[126:127], v[164:165] op_sel_hi:[1,0]
	v_pk_mul_f32 v[124:125], v[124:125], v[164:165] op_sel_hi:[1,0]
	v_pk_mul_f32 v[122:123], v[122:123], v[164:165] op_sel_hi:[1,0]
	v_pk_mul_f32 v[120:121], v[120:121], v[164:165] op_sel_hi:[1,0]
	v_pk_mul_f32 v[114:115], v[114:115], v[164:165] op_sel_hi:[1,0]
	v_pk_mul_f32 v[112:113], v[112:113], v[164:165] op_sel_hi:[1,0]
	v_pk_mul_f32 v[118:119], v[118:119], v[164:165] op_sel_hi:[1,0]
	v_pk_mul_f32 v[116:117], v[116:117], v[164:165] op_sel_hi:[1,0]
	v_max_f32_e32 v124, 0, v124
	v_max_f32_e32 v120, 0, v120
	v_max_f32_e32 v125, 0, v125
	v_max_f32_e32 v121, 0, v121
	v_max_f32_e32 v126, 0, v126
	v_max_f32_e32 v122, 0, v122
	v_max_f32_e32 v127, 0, v127
	v_max_f32_e32 v123, 0, v123
	v_max_f32_e32 v112, 0, v112
	v_max_f32_e32 v113, 0, v113
	v_max_f32_e32 v114, 0, v114
	v_max_f32_e32 v115, 0, v115
	v_max_f32_e32 v116, 0, v116
	v_max_f32_e32 v117, 0, v117
	v_max_f32_e32 v118, 0, v118
	v_max_f32_e32 v119, 0, v119
	v_mul_f32_e32 v124, v124, v124
	v_mul_f32_e32 v120, v120, v120
	v_mul_f32_e32 v125, v125, v125
	v_mul_f32_e32 v121, v121, v121
	v_mul_f32_e32 v126, v126, v126
	v_mul_f32_e32 v122, v122, v122
	v_mul_f32_e32 v127, v127, v127
	v_mul_f32_e32 v123, v123, v123
	v_mul_f32_e32 v149, v112, v112
	v_mul_f32_e32 v164, v113, v113
	v_mul_f32_e32 v165, v114, v114
	v_mul_f32_e32 v166, v115, v115
	v_cvt_pk_bf16_f32 v112, v124, v125
	v_cvt_pk_bf16_f32 v113, v126, v127
	v_cvt_pk_bf16_f32 v114, v120, v121
	v_cvt_pk_bf16_f32 v115, v122, v123
	v_mul_f32_e32 v116, v116, v116
	v_mul_f32_e32 v117, v117, v117
	v_mul_f32_e32 v118, v118, v118
	v_mul_f32_e32 v119, v119, v119
	global_store_dwordx4 v[146:147], v[112:115], off sc0 sc1
	s_nop 1
	v_cvt_pk_bf16_f32 v112, v116, v117
	v_cvt_pk_bf16_f32 v113, v118, v119
	v_cvt_pk_bf16_f32 v114, v149, v164
	v_cvt_pk_bf16_f32 v115, v165, v166
	global_store_dwordx4 v[146:147], v[112:115], off offset:256 sc0 sc1
	global_load_dword v116, v[162:163], off
	s_waitcnt vmcnt(0)
	v_fmamk_f32 v116, v116, 0x3a000000, v159
	v_mul_f32_e32 v117, 0x4b800000, v116
	v_cmp_gt_f32_e32 vcc, s56, v116
	v_lshlrev_b64 v[114:115], 14, v[160:161]
	v_or_b32_e32 v112, 32, v148
	v_cndmask_b32_e32 v116, v116, v117, vcc
	v_rsq_f32_e32 v118, v116
	v_lshl_add_u64 v[114:115], s[6:7], 0, v[114:115]
	v_ashrrev_i32_e32 v113, 31, v112
	v_lshl_add_u64 v[114:115], v[114:115], 0, v[150:151]
	v_mul_f32_e32 v119, 0x45800000, v118
	v_cndmask_b32_e32 v118, v118, v119, vcc
	v_pk_mul_f32 v[110:111], v[110:111], v[118:119] op_sel_hi:[1,0]
	v_pk_mul_f32 v[108:109], v[108:109], v[118:119] op_sel_hi:[1,0]
	v_pk_mul_f32 v[106:107], v[106:107], v[118:119] op_sel_hi:[1,0]
	v_pk_mul_f32 v[104:105], v[104:105], v[118:119] op_sel_hi:[1,0]
	v_pk_mul_f32 v[98:99], v[98:99], v[118:119] op_sel_hi:[1,0]
	v_pk_mul_f32 v[96:97], v[96:97], v[118:119] op_sel_hi:[1,0]
	v_pk_mul_f32 v[102:103], v[102:103], v[118:119] op_sel_hi:[1,0]
	v_pk_mul_f32 v[100:101], v[100:101], v[118:119] op_sel_hi:[1,0]
	v_max_f32_e32 v108, 0, v108
	v_max_f32_e32 v104, 0, v104
	v_max_f32_e32 v109, 0, v109
	v_max_f32_e32 v105, 0, v105
	v_max_f32_e32 v110, 0, v110
	v_max_f32_e32 v106, 0, v106
	v_max_f32_e32 v111, 0, v111
	v_max_f32_e32 v107, 0, v107
	v_max_f32_e32 v96, 0, v96
	v_max_f32_e32 v97, 0, v97
	v_max_f32_e32 v98, 0, v98
	v_max_f32_e32 v99, 0, v99
	v_max_f32_e32 v100, 0, v100
	v_max_f32_e32 v101, 0, v101
	v_max_f32_e32 v102, 0, v102
	v_max_f32_e32 v103, 0, v103
	v_mul_f32_e32 v108, v108, v108
	v_mul_f32_e32 v104, v104, v104
	v_mul_f32_e32 v109, v109, v109
	v_mul_f32_e32 v105, v105, v105
	v_mul_f32_e32 v110, v110, v110
	v_mul_f32_e32 v106, v106, v106
	v_mul_f32_e32 v111, v111, v111
	v_mul_f32_e32 v107, v107, v107
	v_mul_f32_e32 v118, v96, v96
	v_mul_f32_e32 v119, v97, v97
	v_mul_f32_e32 v120, v98, v98
	v_mul_f32_e32 v121, v99, v99
	v_cvt_pk_bf16_f32 v96, v108, v109
	v_cvt_pk_bf16_f32 v97, v110, v111
	v_cvt_pk_bf16_f32 v98, v104, v105
	v_cvt_pk_bf16_f32 v99, v106, v107
	v_lshl_add_u64 v[116:117], v[112:113], 2, s[8:9]
	v_mul_f32_e32 v100, v100, v100
	v_mul_f32_e32 v101, v101, v101
	v_mul_f32_e32 v102, v102, v102
	v_mul_f32_e32 v103, v103, v103
	global_store_dwordx4 v[114:115], v[96:99], off sc0 sc1
	s_nop 1
	v_cvt_pk_bf16_f32 v96, v100, v101
	v_cvt_pk_bf16_f32 v97, v102, v103
	v_cvt_pk_bf16_f32 v98, v118, v119
	v_cvt_pk_bf16_f32 v99, v120, v121
	global_store_dwordx4 v[114:115], v[96:99], off offset:256 sc0 sc1
	global_load_dword v100, v[116:117], off
	s_waitcnt vmcnt(0)
	v_fmamk_f32 v100, v100, 0x3a000000, v159
	v_mul_f32_e32 v101, 0x4b800000, v100
	v_cmp_gt_f32_e32 vcc, s56, v100
	v_lshlrev_b64 v[98:99], 14, v[112:113]
	v_or_b32_e32 v96, 48, v148
	v_cndmask_b32_e32 v100, v100, v101, vcc
	v_rsq_f32_e32 v102, v100
	v_lshl_add_u64 v[98:99], s[6:7], 0, v[98:99]
	v_ashrrev_i32_e32 v97, 31, v96
	v_lshl_add_u64 v[98:99], v[98:99], 0, v[150:151]
	v_mul_f32_e32 v103, 0x45800000, v102
	v_cndmask_b32_e32 v102, v102, v103, vcc
	v_pk_mul_f32 v[94:95], v[94:95], v[102:103] op_sel_hi:[1,0]
	v_pk_mul_f32 v[92:93], v[92:93], v[102:103] op_sel_hi:[1,0]
	v_pk_mul_f32 v[90:91], v[90:91], v[102:103] op_sel_hi:[1,0]
	v_pk_mul_f32 v[88:89], v[88:89], v[102:103] op_sel_hi:[1,0]
	v_pk_mul_f32 v[82:83], v[82:83], v[102:103] op_sel_hi:[1,0]
	v_pk_mul_f32 v[80:81], v[80:81], v[102:103] op_sel_hi:[1,0]
	v_pk_mul_f32 v[86:87], v[86:87], v[102:103] op_sel_hi:[1,0]
	v_pk_mul_f32 v[84:85], v[84:85], v[102:103] op_sel_hi:[1,0]
	v_max_f32_e32 v92, 0, v92
	v_max_f32_e32 v88, 0, v88
	v_max_f32_e32 v93, 0, v93
	v_max_f32_e32 v89, 0, v89
	v_max_f32_e32 v94, 0, v94
	v_max_f32_e32 v90, 0, v90
	v_max_f32_e32 v95, 0, v95
	v_max_f32_e32 v91, 0, v91
	v_max_f32_e32 v80, 0, v80
	v_max_f32_e32 v81, 0, v81
	v_max_f32_e32 v82, 0, v82
	v_max_f32_e32 v83, 0, v83
	v_max_f32_e32 v84, 0, v84
	v_max_f32_e32 v85, 0, v85
	v_max_f32_e32 v86, 0, v86
	v_max_f32_e32 v87, 0, v87
	v_mul_f32_e32 v92, v92, v92
	v_mul_f32_e32 v88, v88, v88
	v_mul_f32_e32 v93, v93, v93
	v_mul_f32_e32 v89, v89, v89
	v_mul_f32_e32 v94, v94, v94
	v_mul_f32_e32 v90, v90, v90
	v_mul_f32_e32 v95, v95, v95
	v_mul_f32_e32 v91, v91, v91
	v_mul_f32_e32 v102, v80, v80
	v_mul_f32_e32 v103, v81, v81
	v_mul_f32_e32 v104, v82, v82
	v_mul_f32_e32 v105, v83, v83
	v_cvt_pk_bf16_f32 v80, v92, v93
	v_cvt_pk_bf16_f32 v81, v94, v95
	v_cvt_pk_bf16_f32 v82, v88, v89
	v_cvt_pk_bf16_f32 v83, v90, v91
	v_lshl_add_u64 v[100:101], v[96:97], 2, s[8:9]
	v_mul_f32_e32 v84, v84, v84
	v_mul_f32_e32 v85, v85, v85
	v_mul_f32_e32 v86, v86, v86
	v_mul_f32_e32 v87, v87, v87
	global_store_dwordx4 v[98:99], v[80:83], off sc0 sc1
	s_nop 1
	v_cvt_pk_bf16_f32 v80, v84, v85
	v_cvt_pk_bf16_f32 v81, v86, v87
	v_cvt_pk_bf16_f32 v82, v102, v103
	v_cvt_pk_bf16_f32 v83, v104, v105
	global_store_dwordx4 v[98:99], v[80:83], off offset:256 sc0 sc1
	global_load_dword v80, v[100:101], off
	s_waitcnt vmcnt(0)
	v_fmamk_f32 v80, v80, 0x3a000000, v159
	v_mul_f32_e32 v81, 0x4b800000, v80
	v_cmp_gt_f32_e32 vcc, s56, v80
	s_nop 1
	v_cndmask_b32_e32 v80, v80, v81, vcc
	v_rsq_f32_e32 v82, v80
	v_lshlrev_b64 v[80:81], 14, v[96:97]
	v_lshl_add_u64 v[80:81], s[6:7], 0, v[80:81]
	v_lshl_add_u64 v[80:81], v[80:81], 0, v[150:151]
	v_mul_f32_e32 v83, 0x45800000, v82
	v_cndmask_b32_e32 v82, v82, v83, vcc
	v_pk_mul_f32 v[78:79], v[78:79], v[82:83] op_sel_hi:[1,0]
	v_pk_mul_f32 v[76:77], v[76:77], v[82:83] op_sel_hi:[1,0]
	v_pk_mul_f32 v[74:75], v[74:75], v[82:83] op_sel_hi:[1,0]
	v_pk_mul_f32 v[72:73], v[72:73], v[82:83] op_sel_hi:[1,0]
	v_pk_mul_f32 v[66:67], v[66:67], v[82:83] op_sel_hi:[1,0]
	v_pk_mul_f32 v[64:65], v[64:65], v[82:83] op_sel_hi:[1,0]
	v_pk_mul_f32 v[70:71], v[70:71], v[82:83] op_sel_hi:[1,0]
	v_pk_mul_f32 v[68:69], v[68:69], v[82:83] op_sel_hi:[1,0]
	v_max_f32_e32 v76, 0, v76
	v_max_f32_e32 v72, 0, v72
	v_max_f32_e32 v77, 0, v77
	v_max_f32_e32 v73, 0, v73
	v_max_f32_e32 v78, 0, v78
	v_max_f32_e32 v74, 0, v74
	v_max_f32_e32 v79, 0, v79
	v_max_f32_e32 v75, 0, v75
	v_max_f32_e32 v64, 0, v64
	v_max_f32_e32 v65, 0, v65
	v_max_f32_e32 v66, 0, v66
	v_max_f32_e32 v67, 0, v67
	v_max_f32_e32 v68, 0, v68
	v_max_f32_e32 v69, 0, v69
	v_max_f32_e32 v70, 0, v70
	v_max_f32_e32 v71, 0, v71
	v_mul_f32_e32 v76, v76, v76
	v_mul_f32_e32 v72, v72, v72
	v_mul_f32_e32 v77, v77, v77
	v_mul_f32_e32 v73, v73, v73
	v_mul_f32_e32 v78, v78, v78
	v_mul_f32_e32 v74, v74, v74
	v_mul_f32_e32 v79, v79, v79
	v_mul_f32_e32 v75, v75, v75
	v_mul_f32_e32 v82, v64, v64
	v_mul_f32_e32 v83, v65, v65
	v_mul_f32_e32 v84, v66, v66
	v_mul_f32_e32 v85, v67, v67
	v_cvt_pk_bf16_f32 v64, v76, v77
	v_cvt_pk_bf16_f32 v65, v78, v79
	v_cvt_pk_bf16_f32 v66, v72, v73
	v_cvt_pk_bf16_f32 v67, v74, v75
	v_mul_f32_e32 v68, v68, v68
	v_mul_f32_e32 v69, v69, v69
	v_mul_f32_e32 v70, v70, v70
	v_mul_f32_e32 v71, v71, v71
	global_store_dwordx4 v[80:81], v[64:67], off sc0 sc1
	s_nop 1
	v_cvt_pk_bf16_f32 v64, v68, v69
	v_cvt_pk_bf16_f32 v65, v70, v71
	v_cvt_pk_bf16_f32 v66, v82, v83
	v_cvt_pk_bf16_f32 v67, v84, v85
	global_store_dwordx4 v[80:81], v[64:67], off offset:256 sc0 sc1
	global_load_dword v66, v[144:145], off offset:512
	s_nop 0
	v_lshl_add_u64 v[64:65], v[146:147], 0, s[14:15]
	s_waitcnt vmcnt(0)
	v_fmamk_f32 v66, v66, 0x3a000000, v159
	v_mul_f32_e32 v67, 0x4b800000, v66
	v_cmp_gt_f32_e32 vcc, s56, v66
	s_nop 1
	v_cndmask_b32_e32 v66, v66, v67, vcc
	v_rsq_f32_e32 v68, v66
	v_add_co_u32_e64 v66, s[2:3], s57, v146
	v_mul_f32_e32 v69, 0x45800000, v68
	v_cndmask_b32_e32 v68, v68, v69, vcc
	v_pk_mul_f32 v[62:63], v[62:63], v[68:69] op_sel_hi:[1,0]
	v_pk_mul_f32 v[60:61], v[60:61], v[68:69] op_sel_hi:[1,0]
	v_pk_mul_f32 v[58:59], v[58:59], v[68:69] op_sel_hi:[1,0]
	v_pk_mul_f32 v[56:57], v[56:57], v[68:69] op_sel_hi:[1,0]
	v_pk_mul_f32 v[50:51], v[50:51], v[68:69] op_sel_hi:[1,0]
	v_pk_mul_f32 v[48:49], v[48:49], v[68:69] op_sel_hi:[1,0]
	v_pk_mul_f32 v[54:55], v[54:55], v[68:69] op_sel_hi:[1,0]
	v_pk_mul_f32 v[52:53], v[52:53], v[68:69] op_sel_hi:[1,0]
	v_max_f32_e32 v60, 0, v60
	v_max_f32_e32 v56, 0, v56
	v_max_f32_e32 v61, 0, v61
	v_max_f32_e32 v57, 0, v57
	v_max_f32_e32 v62, 0, v62
	v_max_f32_e32 v58, 0, v58
	v_max_f32_e32 v63, 0, v63
	v_max_f32_e32 v59, 0, v59
	v_max_f32_e32 v48, 0, v48
	v_max_f32_e32 v49, 0, v49
	v_max_f32_e32 v50, 0, v50
	v_max_f32_e32 v51, 0, v51
	v_addc_co_u32_e64 v67, s[2:3], 0, v147, s[2:3]
	v_max_f32_e32 v52, 0, v52
	v_max_f32_e32 v53, 0, v53
	v_max_f32_e32 v54, 0, v54
	v_max_f32_e32 v55, 0, v55
	v_mul_f32_e32 v60, v60, v60
	v_mul_f32_e32 v56, v56, v56
	v_mul_f32_e32 v61, v61, v61
	v_mul_f32_e32 v57, v57, v57
	v_mul_f32_e32 v62, v62, v62
	v_mul_f32_e32 v58, v58, v58
	v_mul_f32_e32 v63, v63, v63
	v_mul_f32_e32 v59, v59, v59
	v_mul_f32_e32 v68, v48, v48
	v_mul_f32_e32 v69, v49, v49
	v_mul_f32_e32 v70, v50, v50
	v_mul_f32_e32 v71, v51, v51
	v_cvt_pk_bf16_f32 v48, v60, v61
	v_cvt_pk_bf16_f32 v49, v62, v63
	v_cvt_pk_bf16_f32 v50, v56, v57
	v_cvt_pk_bf16_f32 v51, v58, v59
	v_mul_f32_e32 v52, v52, v52
	v_mul_f32_e32 v53, v53, v53
	v_mul_f32_e32 v54, v54, v54
	v_mul_f32_e32 v55, v55, v55
	global_store_dwordx4 v[66:67], v[48:51], off sc0 sc1
	s_nop 1
	v_cvt_pk_bf16_f32 v48, v52, v53
	v_cvt_pk_bf16_f32 v49, v54, v55
	v_cvt_pk_bf16_f32 v50, v68, v69
	v_cvt_pk_bf16_f32 v51, v70, v71
	global_store_dwordx4 v[64:65], v[48:51], off offset:256 sc0 sc1
	global_load_dword v50, v[144:145], off offset:576
	s_nop 0
	v_lshl_add_u64 v[48:49], v[146:147], 0, s[16:17]
	s_waitcnt vmcnt(0)
	v_fmamk_f32 v50, v50, 0x3a000000, v159
	v_mul_f32_e32 v51, 0x4b800000, v50
	v_cmp_gt_f32_e32 vcc, s56, v50
	s_nop 1
	v_cndmask_b32_e32 v50, v50, v51, vcc
	v_rsq_f32_e32 v52, v50
	v_add_co_u32_e64 v50, s[2:3], s58, v146
	v_mul_f32_e32 v53, 0x45800000, v52
	v_cndmask_b32_e32 v52, v52, v53, vcc
	v_pk_mul_f32 v[46:47], v[46:47], v[52:53] op_sel_hi:[1,0]
	v_pk_mul_f32 v[44:45], v[44:45], v[52:53] op_sel_hi:[1,0]
	v_pk_mul_f32 v[42:43], v[42:43], v[52:53] op_sel_hi:[1,0]
	v_pk_mul_f32 v[40:41], v[40:41], v[52:53] op_sel_hi:[1,0]
	v_pk_mul_f32 v[34:35], v[34:35], v[52:53] op_sel_hi:[1,0]
	v_pk_mul_f32 v[32:33], v[32:33], v[52:53] op_sel_hi:[1,0]
	v_pk_mul_f32 v[38:39], v[38:39], v[52:53] op_sel_hi:[1,0]
	v_pk_mul_f32 v[36:37], v[36:37], v[52:53] op_sel_hi:[1,0]
	v_max_f32_e32 v44, 0, v44
	v_max_f32_e32 v40, 0, v40
	v_max_f32_e32 v45, 0, v45
	v_max_f32_e32 v41, 0, v41
	v_max_f32_e32 v46, 0, v46
	v_max_f32_e32 v42, 0, v42
	v_max_f32_e32 v47, 0, v47
	v_max_f32_e32 v43, 0, v43
	v_max_f32_e32 v32, 0, v32
	v_max_f32_e32 v33, 0, v33
	v_max_f32_e32 v34, 0, v34
	v_max_f32_e32 v35, 0, v35
	v_addc_co_u32_e64 v51, s[2:3], 0, v147, s[2:3]
	v_max_f32_e32 v36, 0, v36
	v_max_f32_e32 v37, 0, v37
	v_max_f32_e32 v38, 0, v38
	v_max_f32_e32 v39, 0, v39
	v_mul_f32_e32 v44, v44, v44
	v_mul_f32_e32 v40, v40, v40
	v_mul_f32_e32 v45, v45, v45
	v_mul_f32_e32 v41, v41, v41
	v_mul_f32_e32 v46, v46, v46
	v_mul_f32_e32 v42, v42, v42
	v_mul_f32_e32 v47, v47, v47
	v_mul_f32_e32 v43, v43, v43
	v_mul_f32_e32 v52, v32, v32
	v_mul_f32_e32 v53, v33, v33
	v_mul_f32_e32 v54, v34, v34
	v_mul_f32_e32 v55, v35, v35
	v_cvt_pk_bf16_f32 v32, v44, v45
	v_cvt_pk_bf16_f32 v33, v46, v47
	v_cvt_pk_bf16_f32 v34, v40, v41
	v_cvt_pk_bf16_f32 v35, v42, v43
	v_mul_f32_e32 v36, v36, v36
	v_mul_f32_e32 v37, v37, v37
	v_mul_f32_e32 v38, v38, v38
	v_mul_f32_e32 v39, v39, v39
	global_store_dwordx4 v[50:51], v[32:35], off sc0 sc1
	s_nop 1
	v_cvt_pk_bf16_f32 v32, v36, v37
	v_cvt_pk_bf16_f32 v33, v38, v39
	v_cvt_pk_bf16_f32 v34, v52, v53
	v_cvt_pk_bf16_f32 v35, v54, v55
	global_store_dwordx4 v[48:49], v[32:35], off offset:256 sc0 sc1
	global_load_dword v34, v[144:145], off offset:640
	s_nop 0
	v_lshl_add_u64 v[32:33], v[146:147], 0, s[18:19]
	s_waitcnt vmcnt(0)
	v_fmamk_f32 v34, v34, 0x3a000000, v159
	v_mul_f32_e32 v35, 0x4b800000, v34
	v_cmp_gt_f32_e32 vcc, s56, v34
	s_nop 1
	v_cndmask_b32_e32 v34, v34, v35, vcc
	v_rsq_f32_e32 v36, v34
	v_add_co_u32_e64 v34, s[2:3], s59, v146
	v_mul_f32_e32 v37, 0x45800000, v36
	v_cndmask_b32_e32 v36, v36, v37, vcc
	v_pk_mul_f32 v[30:31], v[30:31], v[36:37] op_sel_hi:[1,0]
	v_pk_mul_f32 v[28:29], v[28:29], v[36:37] op_sel_hi:[1,0]
	v_pk_mul_f32 v[26:27], v[26:27], v[36:37] op_sel_hi:[1,0]
	v_pk_mul_f32 v[24:25], v[24:25], v[36:37] op_sel_hi:[1,0]
	v_pk_mul_f32 v[18:19], v[18:19], v[36:37] op_sel_hi:[1,0]
	v_pk_mul_f32 v[16:17], v[16:17], v[36:37] op_sel_hi:[1,0]
	v_pk_mul_f32 v[22:23], v[22:23], v[36:37] op_sel_hi:[1,0]
	v_pk_mul_f32 v[20:21], v[20:21], v[36:37] op_sel_hi:[1,0]
	v_max_f32_e32 v28, 0, v28
	v_max_f32_e32 v24, 0, v24
	v_max_f32_e32 v29, 0, v29
	v_max_f32_e32 v25, 0, v25
	v_max_f32_e32 v30, 0, v30
	v_max_f32_e32 v26, 0, v26
	v_max_f32_e32 v31, 0, v31
	v_max_f32_e32 v27, 0, v27
	v_max_f32_e32 v16, 0, v16
	v_max_f32_e32 v17, 0, v17
	v_max_f32_e32 v18, 0, v18
	v_max_f32_e32 v19, 0, v19
	v_addc_co_u32_e64 v35, s[2:3], 0, v147, s[2:3]
	v_max_f32_e32 v20, 0, v20
	v_max_f32_e32 v21, 0, v21
	v_max_f32_e32 v22, 0, v22
	v_max_f32_e32 v23, 0, v23
	v_mul_f32_e32 v28, v28, v28
	v_mul_f32_e32 v24, v24, v24
	v_mul_f32_e32 v29, v29, v29
	v_mul_f32_e32 v25, v25, v25
	v_mul_f32_e32 v30, v30, v30
	v_mul_f32_e32 v26, v26, v26
	v_mul_f32_e32 v31, v31, v31
	v_mul_f32_e32 v27, v27, v27
	v_mul_f32_e32 v36, v16, v16
	v_mul_f32_e32 v37, v17, v17
	v_mul_f32_e32 v38, v18, v18
	v_mul_f32_e32 v39, v19, v19
	v_cvt_pk_bf16_f32 v16, v28, v29
	v_cvt_pk_bf16_f32 v17, v30, v31
	v_cvt_pk_bf16_f32 v18, v24, v25
	v_cvt_pk_bf16_f32 v19, v26, v27
	v_mul_f32_e32 v20, v20, v20
	v_mul_f32_e32 v21, v21, v21
	v_mul_f32_e32 v22, v22, v22
	v_mul_f32_e32 v23, v23, v23
	global_store_dwordx4 v[34:35], v[16:19], off sc0 sc1
	s_andn2_b64 vcc, exec, s[0:1]
	s_nop 0
	v_cvt_pk_bf16_f32 v16, v20, v21
	v_cvt_pk_bf16_f32 v17, v22, v23
	v_cvt_pk_bf16_f32 v18, v36, v37
	v_cvt_pk_bf16_f32 v19, v38, v39
	global_store_dwordx4 v[32:33], v[16:19], off offset:256 sc0 sc1
	global_load_dword v18, v[144:145], off offset:704
	s_nop 0
	v_lshl_add_u64 v[16:17], v[146:147], 0, s[20:21]
	s_waitcnt vmcnt(0)
	v_fmamk_f32 v18, v18, 0x3a000000, v159
	v_mul_f32_e32 v19, 0x4b800000, v18
	v_cmp_gt_f32_e64 s[0:1], s56, v18
	s_nop 1
	v_cndmask_b32_e64 v18, v18, v19, s[0:1]
	v_rsq_f32_e32 v20, v18
	v_add_co_u32_e64 v18, s[2:3], s60, v146
	v_mul_f32_e32 v21, 0x45800000, v20
	v_cndmask_b32_e64 v20, v20, v21, s[0:1]
	v_pk_mul_f32 v[14:15], v[14:15], v[20:21] op_sel_hi:[1,0]
	v_pk_mul_f32 v[12:13], v[12:13], v[20:21] op_sel_hi:[1,0]
	v_pk_mul_f32 v[10:11], v[10:11], v[20:21] op_sel_hi:[1,0]
	v_pk_mul_f32 v[8:9], v[8:9], v[20:21] op_sel_hi:[1,0]
	v_pk_mul_f32 v[2:3], v[2:3], v[20:21] op_sel_hi:[1,0]
	v_pk_mul_f32 v[0:1], v[0:1], v[20:21] op_sel_hi:[1,0]
	v_pk_mul_f32 v[6:7], v[6:7], v[20:21] op_sel_hi:[1,0]
	v_pk_mul_f32 v[4:5], v[4:5], v[20:21] op_sel_hi:[1,0]
	v_max_f32_e32 v12, 0, v12
	v_max_f32_e32 v8, 0, v8
	v_max_f32_e32 v13, 0, v13
	v_max_f32_e32 v9, 0, v9
	v_max_f32_e32 v14, 0, v14
	v_max_f32_e32 v10, 0, v10
	v_max_f32_e32 v15, 0, v15
	v_max_f32_e32 v11, 0, v11
	v_max_f32_e32 v0, 0, v0
	v_max_f32_e32 v1, 0, v1
	v_max_f32_e32 v2, 0, v2
	v_max_f32_e32 v3, 0, v3
	v_addc_co_u32_e64 v19, s[2:3], 0, v147, s[2:3]
	v_max_f32_e32 v4, 0, v4
	v_max_f32_e32 v5, 0, v5
	v_max_f32_e32 v6, 0, v6
	v_max_f32_e32 v7, 0, v7
	v_mul_f32_e32 v12, v12, v12
	v_mul_f32_e32 v8, v8, v8
	v_mul_f32_e32 v13, v13, v13
	v_mul_f32_e32 v9, v9, v9
	v_mul_f32_e32 v14, v14, v14
	v_mul_f32_e32 v10, v10, v10
	v_mul_f32_e32 v15, v15, v15
	v_mul_f32_e32 v11, v11, v11
	v_mul_f32_e32 v20, v0, v0
	v_mul_f32_e32 v21, v1, v1
	v_mul_f32_e32 v22, v2, v2
	v_mul_f32_e32 v23, v3, v3
	v_cvt_pk_bf16_f32 v0, v12, v13
	v_cvt_pk_bf16_f32 v1, v14, v15
	v_cvt_pk_bf16_f32 v2, v8, v9
	v_cvt_pk_bf16_f32 v3, v10, v11
	s_mov_b64 s[0:1], -1
	v_mul_f32_e32 v4, v4, v4
	v_mul_f32_e32 v5, v5, v5
	v_mul_f32_e32 v6, v6, v6
	v_mul_f32_e32 v7, v7, v7
	global_store_dwordx4 v[18:19], v[0:3], off sc0 sc1
	s_nop 1
	v_cvt_pk_bf16_f32 v0, v4, v5
	v_cvt_pk_bf16_f32 v1, v6, v7
	v_cvt_pk_bf16_f32 v2, v20, v21
	v_cvt_pk_bf16_f32 v3, v22, v23
	global_store_dwordx4 v[16:17], v[0:3], off offset:256 sc0 sc1
	s_cbranch_vccnz .LBB0_1418
	s_andn2_b64 vcc, exec, s[4:5]
	s_cbranch_vccnz .LBB0_1417
	s_barrier
	s_branch .LBB0_1417
